# K-loops (gate_up, in_proj, down): one loop-invariant LDS base for all four B half-tile buffers, 4 VALU adds per iteration removed from the load segments
# speedup vs baseline: 1.0020x; 1.0020x over previous
.LBB0_97:
	s_ashr_i32 s7, s6, 31
	s_lshl_b64 s[10:11], s[6:7], 19
	v_readlane_b32 s14, v255, 9
	v_readlane_b32 s15, v255, 10
	s_add_u32 s16, s14, s10
	s_addc_u32 s17, s15, s11
	s_and_b64 s[10:11], s[38:39], exec
	s_cselect_b32 s7, s17, s45
	s_cselect_b32 s10, s16, s44
	s_ashr_i32 s5, s4, 31
	s_lshl_b64 s[14:15], s[4:5], 19
	s_add_u32 s40, s26, s14
	s_addc_u32 s41, s27, s15
	s_and_b64 s[14:15], s[38:39], exec
	s_cselect_b32 s5, s41, s47
	s_cselect_b32 s11, s40, s46
	s_add_u32 s44, s44, 0x40080
	s_addc_u32 s45, s45, 0
	s_add_u32 s13, s46, 0x100
	v_mov_b32_e32 v4, 0
	s_addc_u32 s14, s47, 0
	s_mov_b32 s15, -2
	v_mov_b32_e32 v5, v4
	v_mov_b32_e32 v6, v4
	v_mov_b32_e32 v7, v4
	v_mov_b32_e32 v12, v4
	v_mov_b32_e32 v13, v4
	v_mov_b32_e32 v14, v4
	v_mov_b32_e32 v15, v4
	v_mov_b32_e32 v20, v4
	v_mov_b32_e32 v21, v4
	v_mov_b32_e32 v22, v4
	v_mov_b32_e32 v23, v4
	v_mov_b32_e32 v28, v4
	v_mov_b32_e32 v29, v4
	v_mov_b32_e32 v30, v4
	v_mov_b32_e32 v31, v4
	v_mov_b32_e32 v36, v4
	v_mov_b32_e32 v37, v4
	v_mov_b32_e32 v38, v4
	v_mov_b32_e32 v39, v4
	v_mov_b32_e32 v44, v4
	v_mov_b32_e32 v45, v4
	v_mov_b32_e32 v46, v4
	v_mov_b32_e32 v47, v4
	v_mov_b32_e32 v52, v4
	v_mov_b32_e32 v53, v4
	v_mov_b32_e32 v54, v4
	v_mov_b32_e32 v55, v4
	v_mov_b32_e32 v60, v4
	v_mov_b32_e32 v61, v4
	v_mov_b32_e32 v62, v4
	v_mov_b32_e32 v63, v4
	v_mov_b32_e32 v8, v4
	v_mov_b32_e32 v9, v4
	v_mov_b32_e32 v10, v4
	v_mov_b32_e32 v11, v4
	v_mov_b32_e32 v16, v4
	v_mov_b32_e32 v17, v4
	v_mov_b32_e32 v18, v4
	v_mov_b32_e32 v19, v4
	v_mov_b32_e32 v24, v4
	v_mov_b32_e32 v25, v4
	v_mov_b32_e32 v26, v4
	v_mov_b32_e32 v27, v4
	v_mov_b32_e32 v32, v4
	v_mov_b32_e32 v33, v4
	v_mov_b32_e32 v34, v4
	v_mov_b32_e32 v35, v4
	v_mov_b32_e32 v40, v4
	v_mov_b32_e32 v41, v4
	v_mov_b32_e32 v42, v4
	v_mov_b32_e32 v43, v4
	v_mov_b32_e32 v48, v4
	v_mov_b32_e32 v49, v4
	v_mov_b32_e32 v50, v4
	v_mov_b32_e32 v51, v4
	v_mov_b32_e32 v56, v4
	v_mov_b32_e32 v57, v4
	v_mov_b32_e32 v58, v4
	v_mov_b32_e32 v59, v4
	v_mov_b32_e32 v64, v4
	v_mov_b32_e32 v65, v4
	v_mov_b32_e32 v66, v4
	v_mov_b32_e32 v67, v4
	v_mov_b32_e32 v68, v4
	v_mov_b32_e32 v69, v4
	v_mov_b32_e32 v70, v4
	v_mov_b32_e32 v71, v4
	v_mov_b32_e32 v76, v4
	v_mov_b32_e32 v77, v4
	v_mov_b32_e32 v78, v4
	v_mov_b32_e32 v79, v4
	v_mov_b32_e32 v84, v4
	v_mov_b32_e32 v85, v4
	v_mov_b32_e32 v86, v4
	v_mov_b32_e32 v87, v4
	v_mov_b32_e32 v92, v4
	v_mov_b32_e32 v93, v4
	v_mov_b32_e32 v94, v4
	v_mov_b32_e32 v95, v4
	v_mov_b32_e32 v100, v4
	v_mov_b32_e32 v101, v4
	v_mov_b32_e32 v102, v4
	v_mov_b32_e32 v103, v4
	v_mov_b32_e32 v108, v4
	v_mov_b32_e32 v109, v4
	v_mov_b32_e32 v110, v4
	v_mov_b32_e32 v111, v4
	v_mov_b32_e32 v116, v4
	v_mov_b32_e32 v117, v4
	v_mov_b32_e32 v118, v4
	v_mov_b32_e32 v119, v4
	v_mov_b32_e32 v124, v4
	v_mov_b32_e32 v125, v4
	v_mov_b32_e32 v126, v4
	v_mov_b32_e32 v127, v4
	v_mov_b32_e32 v72, v4
	v_mov_b32_e32 v73, v4
	v_mov_b32_e32 v74, v4
	v_mov_b32_e32 v75, v4
	v_mov_b32_e32 v80, v4
	v_mov_b32_e32 v81, v4
	v_mov_b32_e32 v82, v4
	v_mov_b32_e32 v83, v4
	v_mov_b32_e32 v88, v4
	v_mov_b32_e32 v89, v4
	v_mov_b32_e32 v90, v4
	v_mov_b32_e32 v91, v4
	v_mov_b32_e32 v96, v4
	v_mov_b32_e32 v97, v4
	v_mov_b32_e32 v98, v4
	v_mov_b32_e32 v99, v4
	v_mov_b32_e32 v104, v4
	v_mov_b32_e32 v105, v4
	v_mov_b32_e32 v106, v4
	v_mov_b32_e32 v107, v4
	v_mov_b32_e32 v112, v4
	v_mov_b32_e32 v113, v4
	v_mov_b32_e32 v114, v4
	v_mov_b32_e32 v115, v4
	v_mov_b32_e32 v120, v4
	v_mov_b32_e32 v121, v4
	v_mov_b32_e32 v122, v4
	v_mov_b32_e32 v123, v4
	v_mov_b32_e32 v128, v4
	v_mov_b32_e32 v129, v4
	v_mov_b32_e32 v130, v4
	v_mov_b32_e32 v131, v4
	v_add_u32_e32 v240, 0x10000, v150
.LBB0_98:
	s_add_u32 s18, s44, 0xfffc0080
	s_addc_u32 s19, s45, -1
	s_add_i32 s46, 0, 0x10000
	s_cmp_eq_u32 s15, 12
	s_cselect_b32 s25, s7, s19
	s_cselect_b32 s24, s10, s18
	s_cselect_b32 s23, s5, s14
	s_cselect_b32 s22, s11, s13
	s_add_i32 s47, 0, 0x14000
	ds_read_b128 v[156:159], v240
	ds_read_b128 v[160:163], v240 offset:1024
	ds_read_b128 v[164:167], v240 offset:2048
	ds_read_b128 v[168:171], v240 offset:3072
	ds_read_b128 v[172:175], v240 offset:16384
	ds_read_b128 v[176:179], v240 offset:17408
	ds_read_b128 v[180:183], v240 offset:18432
	ds_read_b128 v[184:187], v240 offset:19456
	s_add_i32 m0, s29, 0xc000
	ds_read_b128 v[208:211], v155
	ds_read_b128 v[212:215], v155 offset:1024
	ds_read_b128 v[216:219], v155 offset:2048
	ds_read_b128 v[220:223], v155 offset:3072
	ds_read_b128 v[224:227], v155 offset:4096
	ds_read_b128 v[228:231], v155 offset:5120
	ds_read_b128 v[232:235], v155 offset:6144
	ds_read_b128 v[236:239], v155 offset:7168
	global_load_lds_dwordx4 v144, s[44:45]
	s_add_i32 m0, s29, 0xe000
	s_nop 0
	global_load_lds_dwordx4 v146, s[44:45]
	s_waitcnt vmcnt(8)
	s_waitcnt lgkmcnt(0)
	s_barrier
	s_setprio 1
	s_waitcnt lgkmcnt(0)
	v_mfma_f32_16x16x32_bf16 v[128:131], v[156:159], v[208:211], v[128:131]
	v_mfma_f32_16x16x32_bf16 v[120:123], v[164:167], v[208:211], v[120:123]
	v_mfma_f32_16x16x32_bf16 v[112:115], v[156:159], v[216:219], v[112:115]
	v_mfma_f32_16x16x32_bf16 v[104:107], v[164:167], v[216:219], v[104:107]
	v_mfma_f32_16x16x32_bf16 v[96:99], v[156:159], v[224:227], v[96:99]
	v_mfma_f32_16x16x32_bf16 v[88:91], v[164:167], v[224:227], v[88:91]
	v_mfma_f32_16x16x32_bf16 v[80:83], v[156:159], v[232:235], v[80:83]
	v_mfma_f32_16x16x32_bf16 v[72:75], v[164:167], v[232:235], v[72:75]
	v_mfma_f32_16x16x32_bf16 v[128:131], v[160:163], v[212:215], v[128:131]
	v_mfma_f32_16x16x32_bf16 v[120:123], v[168:171], v[212:215], v[120:123]
	v_mfma_f32_16x16x32_bf16 v[112:115], v[160:163], v[220:223], v[112:115]
	v_mfma_f32_16x16x32_bf16 v[104:107], v[168:171], v[220:223], v[104:107]
	v_mfma_f32_16x16x32_bf16 v[96:99], v[160:163], v[228:231], v[96:99]
	v_mfma_f32_16x16x32_bf16 v[88:91], v[168:171], v[228:231], v[88:91]
	v_mfma_f32_16x16x32_bf16 v[80:83], v[160:163], v[236:239], v[80:83]
	v_mfma_f32_16x16x32_bf16 v[72:75], v[168:171], v[236:239], v[72:75]
	s_setprio 0
	s_setprio 1
	v_mfma_f32_16x16x32_bf16 v[124:127], v[172:175], v[208:211], v[124:127]
	v_mfma_f32_16x16x32_bf16 v[116:119], v[180:183], v[208:211], v[116:119]
	v_mfma_f32_16x16x32_bf16 v[108:111], v[172:175], v[216:219], v[108:111]
	v_mfma_f32_16x16x32_bf16 v[100:103], v[180:183], v[216:219], v[100:103]
	v_mfma_f32_16x16x32_bf16 v[92:95], v[172:175], v[224:227], v[92:95]
	v_mfma_f32_16x16x32_bf16 v[84:87], v[180:183], v[224:227], v[84:87]
	v_mfma_f32_16x16x32_bf16 v[76:79], v[172:175], v[232:235], v[76:79]
	v_mfma_f32_16x16x32_bf16 v[68:71], v[180:183], v[232:235], v[68:71]
	v_mfma_f32_16x16x32_bf16 v[124:127], v[176:179], v[212:215], v[124:127]
	v_mfma_f32_16x16x32_bf16 v[116:119], v[184:187], v[212:215], v[116:119]
	v_mfma_f32_16x16x32_bf16 v[108:111], v[176:179], v[220:223], v[108:111]
	v_mfma_f32_16x16x32_bf16 v[100:103], v[184:187], v[220:223], v[100:103]
	v_mfma_f32_16x16x32_bf16 v[92:95], v[176:179], v[228:231], v[92:95]
	v_mfma_f32_16x16x32_bf16 v[84:87], v[184:187], v[228:231], v[84:87]
	v_mfma_f32_16x16x32_bf16 v[76:79], v[176:179], v[236:239], v[76:79]
	v_mfma_f32_16x16x32_bf16 v[68:71], v[184:187], v[236:239], v[68:71]
	s_setprio 0
	s_barrier
	s_add_i32 s18, s46, s28
	s_mov_b32 m0, s18
	ds_read_b128 v[208:211], v155 offset:16384
	ds_read_b128 v[212:215], v155 offset:17408
	ds_read_b128 v[216:219], v155 offset:18432
	ds_read_b128 v[220:223], v155 offset:19456
	ds_read_b128 v[224:227], v155 offset:20480
	ds_read_b128 v[228:231], v155 offset:21504
	ds_read_b128 v[232:235], v155 offset:22528
	ds_read_b128 v[236:239], v155 offset:23552
	global_load_lds_dwordx4 v2, s[22:23]
	s_add_i32 m0, s18, 0x2000
	s_add_u32 s18, s22, 0x40000
	s_addc_u32 s19, s23, 0
	s_add_i32 s46, s47, s28
	global_load_lds_dwordx4 v142, s[22:23]
	s_mov_b32 m0, s46
	s_nop 0
	global_load_lds_dwordx4 v2, s[18:19]
	s_add_i32 m0, s46, 0x2000
	s_nop 0
	global_load_lds_dwordx4 v142, s[18:19]
	s_mov_b32 m0, s29
	s_nop 0
	global_load_lds_dwordx4 v0, s[24:25]
	s_mov_b32 m0, s43
	s_nop 0
	global_load_lds_dwordx4 v140, s[24:25]
	s_waitcnt vmcnt(8)
	s_waitcnt lgkmcnt(0)
	s_barrier
	s_setprio 1
	s_waitcnt lgkmcnt(0)
	v_mfma_f32_16x16x32_bf16 v[64:67], v[156:159], v[208:211], v[64:67]
	v_mfma_f32_16x16x32_bf16 v[56:59], v[164:167], v[208:211], v[56:59]
	v_mfma_f32_16x16x32_bf16 v[48:51], v[156:159], v[216:219], v[48:51]
	v_mfma_f32_16x16x32_bf16 v[40:43], v[164:167], v[216:219], v[40:43]
	v_mfma_f32_16x16x32_bf16 v[32:35], v[156:159], v[224:227], v[32:35]
	v_mfma_f32_16x16x32_bf16 v[24:27], v[164:167], v[224:227], v[24:27]
	v_mfma_f32_16x16x32_bf16 v[16:19], v[156:159], v[232:235], v[16:19]
	v_mfma_f32_16x16x32_bf16 v[8:11], v[164:167], v[232:235], v[8:11]
	v_mfma_f32_16x16x32_bf16 v[64:67], v[160:163], v[212:215], v[64:67]
	v_mfma_f32_16x16x32_bf16 v[56:59], v[168:171], v[212:215], v[56:59]
	v_mfma_f32_16x16x32_bf16 v[48:51], v[160:163], v[220:223], v[48:51]
	v_mfma_f32_16x16x32_bf16 v[40:43], v[168:171], v[220:223], v[40:43]
	v_mfma_f32_16x16x32_bf16 v[32:35], v[160:163], v[228:231], v[32:35]
	v_mfma_f32_16x16x32_bf16 v[24:27], v[168:171], v[228:231], v[24:27]
	v_mfma_f32_16x16x32_bf16 v[16:19], v[160:163], v[236:239], v[16:19]
	v_mfma_f32_16x16x32_bf16 v[8:11], v[168:171], v[236:239], v[8:11]
	s_setprio 0
	s_setprio 1
	v_mfma_f32_16x16x32_bf16 v[60:63], v[172:175], v[208:211], v[60:63]
	v_mfma_f32_16x16x32_bf16 v[52:55], v[180:183], v[208:211], v[52:55]
	v_mfma_f32_16x16x32_bf16 v[44:47], v[172:175], v[216:219], v[44:47]
	v_mfma_f32_16x16x32_bf16 v[36:39], v[180:183], v[216:219], v[36:39]
	v_mfma_f32_16x16x32_bf16 v[28:31], v[172:175], v[224:227], v[28:31]
	v_mfma_f32_16x16x32_bf16 v[20:23], v[180:183], v[224:227], v[20:23]
	v_mfma_f32_16x16x32_bf16 v[12:15], v[172:175], v[232:235], v[12:15]
	v_mfma_f32_16x16x32_bf16 v[4:7], v[180:183], v[232:235], v[4:7]
	v_mfma_f32_16x16x32_bf16 v[60:63], v[176:179], v[212:215], v[60:63]
	v_mfma_f32_16x16x32_bf16 v[52:55], v[184:187], v[212:215], v[52:55]
	v_mfma_f32_16x16x32_bf16 v[44:47], v[176:179], v[220:223], v[44:47]
	v_mfma_f32_16x16x32_bf16 v[36:39], v[184:187], v[220:223], v[36:39]
	v_mfma_f32_16x16x32_bf16 v[28:31], v[176:179], v[228:231], v[28:31]
	v_mfma_f32_16x16x32_bf16 v[20:23], v[184:187], v[228:231], v[20:23]
	v_mfma_f32_16x16x32_bf16 v[12:15], v[176:179], v[236:239], v[12:15]
	v_mfma_f32_16x16x32_bf16 v[4:7], v[184:187], v[236:239], v[4:7]
	s_setprio 0
	s_barrier
	s_add_i32 s46, 0, 0x18000
	s_add_i32 s47, 0, 0x1c000
	ds_read_b128 v[156:159], v240 offset:32768
	ds_read_b128 v[160:163], v240 offset:33792
	ds_read_b128 v[164:167], v240 offset:34816
	ds_read_b128 v[168:171], v240 offset:35840
	ds_read_b128 v[172:175], v240 offset:49152
	ds_read_b128 v[176:179], v240 offset:50176
	ds_read_b128 v[180:183], v240 offset:51200
	ds_read_b128 v[184:187], v240 offset:52224
	s_add_u32 s18, s24, 0x40000
	s_addc_u32 s19, s25, 0
	s_mov_b32 m0, s48
	ds_read_b128 v[208:211], v155 offset:32768
	ds_read_b128 v[212:215], v155 offset:33792
	ds_read_b128 v[216:219], v155 offset:34816
	ds_read_b128 v[220:223], v155 offset:35840
	ds_read_b128 v[224:227], v155 offset:36864
	ds_read_b128 v[228:231], v155 offset:37888
	ds_read_b128 v[232:235], v155 offset:38912
	ds_read_b128 v[236:239], v155 offset:39936
	global_load_lds_dwordx4 v0, s[18:19]
	s_mov_b32 m0, s49
	s_nop 0
	global_load_lds_dwordx4 v140, s[18:19]
	s_waitcnt vmcnt(8)
	s_waitcnt lgkmcnt(0)
	s_barrier
	s_setprio 1
	s_waitcnt lgkmcnt(0)
	v_mfma_f32_16x16x32_bf16 v[128:131], v[156:159], v[208:211], v[128:131]
	v_mfma_f32_16x16x32_bf16 v[120:123], v[164:167], v[208:211], v[120:123]
	v_mfma_f32_16x16x32_bf16 v[112:115], v[156:159], v[216:219], v[112:115]
	v_mfma_f32_16x16x32_bf16 v[104:107], v[164:167], v[216:219], v[104:107]
	v_mfma_f32_16x16x32_bf16 v[96:99], v[156:159], v[224:227], v[96:99]
	v_mfma_f32_16x16x32_bf16 v[88:91], v[164:167], v[224:227], v[88:91]
	v_mfma_f32_16x16x32_bf16 v[80:83], v[156:159], v[232:235], v[80:83]
	v_mfma_f32_16x16x32_bf16 v[72:75], v[164:167], v[232:235], v[72:75]
	v_mfma_f32_16x16x32_bf16 v[128:131], v[160:163], v[212:215], v[128:131]
	v_mfma_f32_16x16x32_bf16 v[120:123], v[168:171], v[212:215], v[120:123]
	v_mfma_f32_16x16x32_bf16 v[112:115], v[160:163], v[220:223], v[112:115]
	v_mfma_f32_16x16x32_bf16 v[104:107], v[168:171], v[220:223], v[104:107]
	v_mfma_f32_16x16x32_bf16 v[96:99], v[160:163], v[228:231], v[96:99]
	v_mfma_f32_16x16x32_bf16 v[88:91], v[168:171], v[228:231], v[88:91]
	v_mfma_f32_16x16x32_bf16 v[80:83], v[160:163], v[236:239], v[80:83]
	v_mfma_f32_16x16x32_bf16 v[72:75], v[168:171], v[236:239], v[72:75]
	s_setprio 0
	s_setprio 1
	v_mfma_f32_16x16x32_bf16 v[124:127], v[172:175], v[208:211], v[124:127]
	v_mfma_f32_16x16x32_bf16 v[116:119], v[180:183], v[208:211], v[116:119]
	v_mfma_f32_16x16x32_bf16 v[108:111], v[172:175], v[216:219], v[108:111]
	v_mfma_f32_16x16x32_bf16 v[100:103], v[180:183], v[216:219], v[100:103]
	v_mfma_f32_16x16x32_bf16 v[92:95], v[172:175], v[224:227], v[92:95]
	v_mfma_f32_16x16x32_bf16 v[84:87], v[180:183], v[224:227], v[84:87]
	v_mfma_f32_16x16x32_bf16 v[76:79], v[172:175], v[232:235], v[76:79]
	v_mfma_f32_16x16x32_bf16 v[68:71], v[180:183], v[232:235], v[68:71]
	v_mfma_f32_16x16x32_bf16 v[124:127], v[176:179], v[212:215], v[124:127]
	v_mfma_f32_16x16x32_bf16 v[116:119], v[184:187], v[212:215], v[116:119]
	v_mfma_f32_16x16x32_bf16 v[108:111], v[176:179], v[220:223], v[108:111]
	v_mfma_f32_16x16x32_bf16 v[100:103], v[184:187], v[220:223], v[100:103]
	v_mfma_f32_16x16x32_bf16 v[92:95], v[176:179], v[228:231], v[92:95]
	v_mfma_f32_16x16x32_bf16 v[84:87], v[184:187], v[228:231], v[84:87]
	v_mfma_f32_16x16x32_bf16 v[76:79], v[176:179], v[236:239], v[76:79]
	v_mfma_f32_16x16x32_bf16 v[68:71], v[184:187], v[236:239], v[68:71]
	s_setprio 0
	s_barrier
	s_add_i32 s18, s46, s28
	s_add_u32 s100, s22, 0x80
	s_addc_u32 s101, s23, 0
	s_mov_b32 m0, s18
	ds_read_b128 v[208:211], v155 offset:49152
	ds_read_b128 v[212:215], v155 offset:50176
	ds_read_b128 v[216:219], v155 offset:51200
	ds_read_b128 v[220:223], v155 offset:52224
	ds_read_b128 v[224:227], v155 offset:53248
	ds_read_b128 v[228:231], v155 offset:54272
	ds_read_b128 v[232:235], v155 offset:55296
	ds_read_b128 v[236:239], v155 offset:56320
	global_load_lds_dwordx4 v2, s[100:101]
	s_add_i32 m0, s18, 0x2000
	s_add_u32 s18, s22, 0x40080
	s_addc_u32 s19, s23, 0
	s_add_i32 s22, s47, s28
	global_load_lds_dwordx4 v142, s[100:101]
	s_mov_b32 m0, s22
	s_nop 0
	global_load_lds_dwordx4 v2, s[18:19]
	s_add_i32 m0, s22, 0x2000
	s_nop 0
	global_load_lds_dwordx4 v142, s[18:19]
	s_add_u32 s100, s24, 0x80
	s_addc_u32 s101, s25, 0
	s_mov_b32 m0, s50
	s_nop 0
	global_load_lds_dwordx4 v0, s[100:101]
	s_mov_b32 m0, s51
	s_nop 0
	global_load_lds_dwordx4 v140, s[100:101]
	s_waitcnt vmcnt(8)
	s_waitcnt lgkmcnt(0)
	s_barrier
	s_setprio 1
	s_waitcnt lgkmcnt(0)
	v_mfma_f32_16x16x32_bf16 v[64:67], v[156:159], v[208:211], v[64:67]
	v_mfma_f32_16x16x32_bf16 v[56:59], v[164:167], v[208:211], v[56:59]
	v_mfma_f32_16x16x32_bf16 v[48:51], v[156:159], v[216:219], v[48:51]
	v_mfma_f32_16x16x32_bf16 v[40:43], v[164:167], v[216:219], v[40:43]
	v_mfma_f32_16x16x32_bf16 v[32:35], v[156:159], v[224:227], v[32:35]
	v_mfma_f32_16x16x32_bf16 v[24:27], v[164:167], v[224:227], v[24:27]
	v_mfma_f32_16x16x32_bf16 v[16:19], v[156:159], v[232:235], v[16:19]
	v_mfma_f32_16x16x32_bf16 v[8:11], v[164:167], v[232:235], v[8:11]
	v_mfma_f32_16x16x32_bf16 v[64:67], v[160:163], v[212:215], v[64:67]
	v_mfma_f32_16x16x32_bf16 v[56:59], v[168:171], v[212:215], v[56:59]
	v_mfma_f32_16x16x32_bf16 v[48:51], v[160:163], v[220:223], v[48:51]
	v_mfma_f32_16x16x32_bf16 v[40:43], v[168:171], v[220:223], v[40:43]
	v_mfma_f32_16x16x32_bf16 v[32:35], v[160:163], v[228:231], v[32:35]
	v_mfma_f32_16x16x32_bf16 v[24:27], v[168:171], v[228:231], v[24:27]
	v_mfma_f32_16x16x32_bf16 v[16:19], v[160:163], v[236:239], v[16:19]
	v_mfma_f32_16x16x32_bf16 v[8:11], v[168:171], v[236:239], v[8:11]
	s_setprio 0
	s_setprio 1
	v_mfma_f32_16x16x32_bf16 v[60:63], v[172:175], v[208:211], v[60:63]
	v_mfma_f32_16x16x32_bf16 v[52:55], v[180:183], v[208:211], v[52:55]
	v_mfma_f32_16x16x32_bf16 v[44:47], v[172:175], v[216:219], v[44:47]
	v_mfma_f32_16x16x32_bf16 v[36:39], v[180:183], v[216:219], v[36:39]
	v_mfma_f32_16x16x32_bf16 v[28:31], v[172:175], v[224:227], v[28:31]
	v_mfma_f32_16x16x32_bf16 v[20:23], v[180:183], v[224:227], v[20:23]
	v_mfma_f32_16x16x32_bf16 v[12:15], v[172:175], v[232:235], v[12:15]
	v_mfma_f32_16x16x32_bf16 v[4:7], v[180:183], v[232:235], v[4:7]
	v_mfma_f32_16x16x32_bf16 v[60:63], v[176:179], v[212:215], v[60:63]
	v_mfma_f32_16x16x32_bf16 v[52:55], v[184:187], v[212:215], v[52:55]
	v_mfma_f32_16x16x32_bf16 v[44:47], v[176:179], v[220:223], v[44:47]
	v_mfma_f32_16x16x32_bf16 v[36:39], v[184:187], v[220:223], v[36:39]
	v_mfma_f32_16x16x32_bf16 v[28:31], v[176:179], v[228:231], v[28:31]
	v_mfma_f32_16x16x32_bf16 v[20:23], v[184:187], v[228:231], v[20:23]
	v_mfma_f32_16x16x32_bf16 v[12:15], v[176:179], v[236:239], v[12:15]
	v_mfma_f32_16x16x32_bf16 v[4:7], v[184:187], v[236:239], v[4:7]
	s_setprio 0
	s_barrier
	s_add_i32 s15, s15, 2
	s_add_u32 s44, s44, 0x100
	s_addc_u32 s45, s45, 0
	s_add_u32 s13, s13, 0x100
	s_addc_u32 s14, s14, 0
	s_cmp_gt_u32 s15, 13
	s_cbranch_scc0 .LBB0_98
	s_lshl_b32 s5, s42, 8
	s_and_b64 vcc, exec, s[2:3]
	s_cbranch_vccz .LBB0_101
	v_or_b32_e32 v148, s5, v152
	v_ashrrev_i32_e32 v149, 31, v148
	v_readlane_b32 s10, v255, 11
	v_lshlrev_b64 v[148:149], 6, v[148:149]
	v_readlane_b32 s11, v255, 12
	s_nop 1
	v_lshl_add_u64 v[148:149], s[10:11], 0, v[148:149]
	global_load_dwordx4 v[156:159], v[148:149], off
	global_load_dwordx4 v[160:163], v[148:149], off offset:32
	global_load_dwordx4 v[164:167], v[148:149], off offset:16
	global_load_dwordx4 v[168:171], v[148:149], off offset:48
	s_barrier

.LBB0_810:
	s_add_u32 s13, s24, 0x100
	v_mov_b32_e32 v4, 0
	s_addc_u32 s14, s25, 0
	s_mov_b32 s15, -2
	v_mov_b32_e32 v5, v4
	v_mov_b32_e32 v6, v4
	v_mov_b32_e32 v7, v4
	v_mov_b32_e32 v8, v4
	s_waitcnt lgkmcnt(0)
	v_mov_b32_e32 v9, v4
	v_mov_b32_e32 v10, v4
	v_mov_b32_e32 v11, v4
	v_mov_b32_e32 v20, v4
	v_mov_b32_e32 v21, v4
	v_mov_b32_e32 v22, v4
	v_mov_b32_e32 v23, v4
	v_mov_b32_e32 v24, v4
	v_mov_b32_e32 v25, v4
	v_mov_b32_e32 v26, v4
	v_mov_b32_e32 v27, v4
	v_mov_b32_e32 v36, v4
	v_mov_b32_e32 v37, v4
	v_mov_b32_e32 v38, v4
	v_mov_b32_e32 v39, v4
	v_mov_b32_e32 v40, v4
	v_mov_b32_e32 v41, v4
	v_mov_b32_e32 v42, v4
	v_mov_b32_e32 v43, v4
	v_mov_b32_e32 v52, v4
	v_mov_b32_e32 v53, v4
	v_mov_b32_e32 v54, v4
	v_mov_b32_e32 v55, v4
	v_mov_b32_e32 v56, v4
	v_mov_b32_e32 v57, v4
	v_mov_b32_e32 v58, v4
	v_mov_b32_e32 v59, v4
	v_mov_b32_e32 v12, v4
	v_mov_b32_e32 v13, v4
	v_mov_b32_e32 v14, v4
	v_mov_b32_e32 v15, v4
	v_mov_b32_e32 v16, v4
	v_mov_b32_e32 v17, v4
	v_mov_b32_e32 v18, v4
	v_mov_b32_e32 v19, v4
	v_mov_b32_e32 v28, v4
	v_mov_b32_e32 v29, v4
	v_mov_b32_e32 v30, v4
	v_mov_b32_e32 v31, v4
	v_mov_b32_e32 v32, v4
	v_mov_b32_e32 v33, v4
	v_mov_b32_e32 v34, v4
	v_mov_b32_e32 v35, v4
	v_mov_b32_e32 v44, v4
	v_mov_b32_e32 v45, v4
	v_mov_b32_e32 v46, v4
	v_mov_b32_e32 v47, v4
	v_mov_b32_e32 v48, v4
	v_mov_b32_e32 v49, v4
	v_mov_b32_e32 v50, v4
	v_mov_b32_e32 v51, v4
	v_mov_b32_e32 v60, v4
	v_mov_b32_e32 v61, v4
	v_mov_b32_e32 v62, v4
	v_mov_b32_e32 v63, v4
	v_mov_b32_e32 v64, v4
	v_mov_b32_e32 v65, v4
	v_mov_b32_e32 v66, v4
	v_mov_b32_e32 v67, v4
	v_mov_b32_e32 v68, v4
	v_mov_b32_e32 v69, v4
	v_mov_b32_e32 v70, v4
	v_mov_b32_e32 v71, v4
	v_mov_b32_e32 v72, v4
	v_mov_b32_e32 v73, v4
	v_mov_b32_e32 v74, v4
	v_mov_b32_e32 v75, v4
	v_mov_b32_e32 v84, v4
	v_mov_b32_e32 v85, v4
	v_mov_b32_e32 v86, v4
	v_mov_b32_e32 v87, v4
	v_mov_b32_e32 v88, v4
	v_mov_b32_e32 v89, v4
	v_mov_b32_e32 v90, v4
	v_mov_b32_e32 v91, v4
	v_mov_b32_e32 v100, v4
	v_mov_b32_e32 v101, v4
	v_mov_b32_e32 v102, v4
	v_mov_b32_e32 v103, v4
	v_mov_b32_e32 v104, v4
	v_mov_b32_e32 v105, v4
	v_mov_b32_e32 v106, v4
	v_mov_b32_e32 v107, v4
	v_mov_b32_e32 v116, v4
	v_mov_b32_e32 v117, v4
	v_mov_b32_e32 v118, v4
	v_mov_b32_e32 v119, v4
	v_mov_b32_e32 v120, v4
	v_mov_b32_e32 v121, v4
	v_mov_b32_e32 v122, v4
	v_mov_b32_e32 v123, v4
	v_mov_b32_e32 v76, v4
	v_mov_b32_e32 v77, v4
	v_mov_b32_e32 v78, v4
	v_mov_b32_e32 v79, v4
	v_mov_b32_e32 v80, v4
	v_mov_b32_e32 v81, v4
	v_mov_b32_e32 v82, v4
	v_mov_b32_e32 v83, v4
	v_mov_b32_e32 v92, v4
	v_mov_b32_e32 v93, v4
	v_mov_b32_e32 v94, v4
	v_mov_b32_e32 v95, v4
	v_mov_b32_e32 v96, v4
	v_mov_b32_e32 v97, v4
	v_mov_b32_e32 v98, v4
	v_mov_b32_e32 v99, v4
	v_mov_b32_e32 v108, v4
	v_mov_b32_e32 v109, v4
	v_mov_b32_e32 v110, v4
	v_mov_b32_e32 v111, v4
	v_mov_b32_e32 v112, v4
	v_mov_b32_e32 v113, v4
	v_mov_b32_e32 v114, v4
	v_mov_b32_e32 v115, v4
	v_mov_b32_e32 v124, v4
	v_mov_b32_e32 v125, v4
	v_mov_b32_e32 v126, v4
	v_mov_b32_e32 v127, v4
	v_mov_b32_e32 v128, v4
	v_mov_b32_e32 v129, v4
	v_mov_b32_e32 v130, v4
	v_mov_b32_e32 v131, v4
	v_add_u32_e32 v213, 0x10000, v210
.LBB0_811:
	s_add_u32 s42, s44, 0x100
	s_addc_u32 s43, s45, 0
	s_add_i32 s18, 0, 0x10000
	s_cmp_eq_u32 s15, 40
	s_cselect_b32 s25, s11, s43
	s_cselect_b32 s24, s10, s42
	s_cselect_b32 s23, s17, s14
	s_cselect_b32 s22, s16, s13
	s_add_i32 s62, 0, 0x14000
	ds_read_b128 v[144:147], v213
	ds_read_b128 v[148:151], v213 offset:1024
	ds_read_b128 v[152:155], v213 offset:2048
	ds_read_b128 v[156:159], v213 offset:3072
	ds_read_b128 v[160:163], v213 offset:16384
	ds_read_b128 v[164:167], v213 offset:17408
	ds_read_b128 v[168:171], v213 offset:18432
	ds_read_b128 v[172:175], v213 offset:19456
	s_add_i32 m0, s47, 0xc000
	ds_read_b128 v[176:179], v212
	ds_read_b128 v[180:183], v212 offset:1024
	ds_read_b128 v[184:187], v212 offset:2048
	ds_read_b128 v[214:217], v212 offset:3072
	ds_read_b128 v[218:221], v212 offset:4096
	ds_read_b128 v[222:225], v212 offset:5120
	ds_read_b128 v[226:229], v212 offset:6144
	ds_read_b128 v[230:233], v212 offset:7168
	global_load_lds_dwordx4 v140, s[44:45]
	s_add_i32 m0, s47, 0xe000
	s_nop 0
	global_load_lds_dwordx4 v142, s[44:45]
	s_waitcnt vmcnt(8)
	s_waitcnt lgkmcnt(0)
	s_barrier
	s_setprio 1
	s_waitcnt lgkmcnt(0)
	v_mfma_f32_16x16x32_bf16 v[128:131], v[144:147], v[176:179], v[128:131]
	v_mfma_f32_16x16x32_bf16 v[124:127], v[152:155], v[176:179], v[124:127]
	v_mfma_f32_16x16x32_bf16 v[112:115], v[144:147], v[184:187], v[112:115]
	v_mfma_f32_16x16x32_bf16 v[108:111], v[152:155], v[184:187], v[108:111]
	v_mfma_f32_16x16x32_bf16 v[96:99], v[144:147], v[218:221], v[96:99]
	v_mfma_f32_16x16x32_bf16 v[92:95], v[152:155], v[218:221], v[92:95]
	v_mfma_f32_16x16x32_bf16 v[80:83], v[144:147], v[226:229], v[80:83]
	v_mfma_f32_16x16x32_bf16 v[76:79], v[152:155], v[226:229], v[76:79]
	v_mfma_f32_16x16x32_bf16 v[128:131], v[148:151], v[180:183], v[128:131]
	v_mfma_f32_16x16x32_bf16 v[124:127], v[156:159], v[180:183], v[124:127]
	v_mfma_f32_16x16x32_bf16 v[112:115], v[148:151], v[214:217], v[112:115]
	v_mfma_f32_16x16x32_bf16 v[108:111], v[156:159], v[214:217], v[108:111]
	v_mfma_f32_16x16x32_bf16 v[96:99], v[148:151], v[222:225], v[96:99]
	v_mfma_f32_16x16x32_bf16 v[92:95], v[156:159], v[222:225], v[92:95]
	v_mfma_f32_16x16x32_bf16 v[80:83], v[148:151], v[230:233], v[80:83]
	v_mfma_f32_16x16x32_bf16 v[76:79], v[156:159], v[230:233], v[76:79]
	s_setprio 0
	s_setprio 1
	v_mfma_f32_16x16x32_bf16 v[120:123], v[160:163], v[176:179], v[120:123]
	v_mfma_f32_16x16x32_bf16 v[116:119], v[168:171], v[176:179], v[116:119]
	v_mfma_f32_16x16x32_bf16 v[104:107], v[160:163], v[184:187], v[104:107]
	v_mfma_f32_16x16x32_bf16 v[100:103], v[168:171], v[184:187], v[100:103]
	v_mfma_f32_16x16x32_bf16 v[88:91], v[160:163], v[218:221], v[88:91]
	v_mfma_f32_16x16x32_bf16 v[84:87], v[168:171], v[218:221], v[84:87]
	v_mfma_f32_16x16x32_bf16 v[72:75], v[160:163], v[226:229], v[72:75]
	v_mfma_f32_16x16x32_bf16 v[68:71], v[168:171], v[226:229], v[68:71]
	v_mfma_f32_16x16x32_bf16 v[120:123], v[164:167], v[180:183], v[120:123]
	v_mfma_f32_16x16x32_bf16 v[116:119], v[172:175], v[180:183], v[116:119]
	v_mfma_f32_16x16x32_bf16 v[104:107], v[164:167], v[214:217], v[104:107]
	v_mfma_f32_16x16x32_bf16 v[100:103], v[172:175], v[214:217], v[100:103]
	v_mfma_f32_16x16x32_bf16 v[88:91], v[164:167], v[222:225], v[88:91]
	v_mfma_f32_16x16x32_bf16 v[84:87], v[172:175], v[222:225], v[84:87]
	v_mfma_f32_16x16x32_bf16 v[72:75], v[164:167], v[230:233], v[72:75]
	v_mfma_f32_16x16x32_bf16 v[68:71], v[172:175], v[230:233], v[68:71]
	s_setprio 0
	s_barrier
	s_add_i32 s18, s18, s46
	s_mov_b32 m0, s18
	ds_read_b128 v[176:179], v212 offset:16384
	ds_read_b128 v[180:183], v212 offset:17408
	ds_read_b128 v[184:187], v212 offset:18432
	ds_read_b128 v[214:217], v212 offset:19456
	ds_read_b128 v[218:221], v212 offset:20480
	ds_read_b128 v[222:225], v212 offset:21504
	ds_read_b128 v[226:229], v212 offset:22528
	ds_read_b128 v[230:233], v212 offset:23552
	global_load_lds_dwordx4 v2, s[22:23]
	s_add_i32 m0, s18, 0x2000
	s_add_u32 s18, s22, 0xb0000
	s_addc_u32 s19, s23, 0
	s_add_i32 s44, s62, s46
	global_load_lds_dwordx4 v0, s[22:23]
	s_mov_b32 m0, s44
	s_nop 0
	global_load_lds_dwordx4 v2, s[18:19]
	s_add_i32 m0, s44, 0x2000
	s_nop 0
	global_load_lds_dwordx4 v0, s[18:19]
	s_mov_b32 m0, s47
	s_nop 0
	global_load_lds_dwordx4 v2, s[24:25]
	s_mov_b32 m0, s48
	s_nop 0
	global_load_lds_dwordx4 v0, s[24:25]
	s_waitcnt vmcnt(8)
	s_waitcnt lgkmcnt(0)
	s_barrier
	s_setprio 1
	s_waitcnt lgkmcnt(0)
	v_mfma_f32_16x16x32_bf16 v[64:67], v[144:147], v[176:179], v[64:67]
	v_mfma_f32_16x16x32_bf16 v[60:63], v[152:155], v[176:179], v[60:63]
	v_mfma_f32_16x16x32_bf16 v[48:51], v[144:147], v[184:187], v[48:51]
	v_mfma_f32_16x16x32_bf16 v[44:47], v[152:155], v[184:187], v[44:47]
	v_mfma_f32_16x16x32_bf16 v[32:35], v[144:147], v[218:221], v[32:35]
	v_mfma_f32_16x16x32_bf16 v[28:31], v[152:155], v[218:221], v[28:31]
	v_mfma_f32_16x16x32_bf16 v[16:19], v[144:147], v[226:229], v[16:19]
	v_mfma_f32_16x16x32_bf16 v[12:15], v[152:155], v[226:229], v[12:15]
	v_mfma_f32_16x16x32_bf16 v[64:67], v[148:151], v[180:183], v[64:67]
	v_mfma_f32_16x16x32_bf16 v[60:63], v[156:159], v[180:183], v[60:63]
	v_mfma_f32_16x16x32_bf16 v[48:51], v[148:151], v[214:217], v[48:51]
	v_mfma_f32_16x16x32_bf16 v[44:47], v[156:159], v[214:217], v[44:47]
	v_mfma_f32_16x16x32_bf16 v[32:35], v[148:151], v[222:225], v[32:35]
	v_mfma_f32_16x16x32_bf16 v[28:31], v[156:159], v[222:225], v[28:31]
	v_mfma_f32_16x16x32_bf16 v[16:19], v[148:151], v[230:233], v[16:19]
	v_mfma_f32_16x16x32_bf16 v[12:15], v[156:159], v[230:233], v[12:15]
	s_setprio 0
	s_setprio 1
	v_mfma_f32_16x16x32_bf16 v[56:59], v[160:163], v[176:179], v[56:59]
	v_mfma_f32_16x16x32_bf16 v[52:55], v[168:171], v[176:179], v[52:55]
	v_mfma_f32_16x16x32_bf16 v[40:43], v[160:163], v[184:187], v[40:43]
	v_mfma_f32_16x16x32_bf16 v[36:39], v[168:171], v[184:187], v[36:39]
	v_mfma_f32_16x16x32_bf16 v[24:27], v[160:163], v[218:221], v[24:27]
	v_mfma_f32_16x16x32_bf16 v[20:23], v[168:171], v[218:221], v[20:23]
	v_mfma_f32_16x16x32_bf16 v[8:11], v[160:163], v[226:229], v[8:11]
	v_mfma_f32_16x16x32_bf16 v[4:7], v[168:171], v[226:229], v[4:7]
	v_mfma_f32_16x16x32_bf16 v[56:59], v[164:167], v[180:183], v[56:59]
	v_mfma_f32_16x16x32_bf16 v[52:55], v[172:175], v[180:183], v[52:55]
	v_mfma_f32_16x16x32_bf16 v[40:43], v[164:167], v[214:217], v[40:43]
	v_mfma_f32_16x16x32_bf16 v[36:39], v[172:175], v[214:217], v[36:39]
	v_mfma_f32_16x16x32_bf16 v[24:27], v[164:167], v[222:225], v[24:27]
	v_mfma_f32_16x16x32_bf16 v[20:23], v[172:175], v[222:225], v[20:23]
	v_mfma_f32_16x16x32_bf16 v[8:11], v[164:167], v[230:233], v[8:11]
	v_mfma_f32_16x16x32_bf16 v[4:7], v[172:175], v[230:233], v[4:7]
	s_setprio 0
	s_barrier
	s_add_i32 s44, 0, 0x18000
	s_add_i32 s45, 0, 0x1c000
	ds_read_b128 v[144:147], v213 offset:32768
	ds_read_b128 v[148:151], v213 offset:33792
	ds_read_b128 v[152:155], v213 offset:34816
	ds_read_b128 v[156:159], v213 offset:35840
	ds_read_b128 v[160:163], v213 offset:49152
	ds_read_b128 v[164:167], v213 offset:50176
	ds_read_b128 v[168:171], v213 offset:51200
	ds_read_b128 v[172:175], v213 offset:52224
	s_add_u32 s18, s24, 0xb0000
	s_addc_u32 s19, s25, 0
	s_mov_b32 m0, s49
	ds_read_b128 v[176:179], v212 offset:32768
	ds_read_b128 v[180:183], v212 offset:33792
	ds_read_b128 v[184:187], v212 offset:34816
	ds_read_b128 v[214:217], v212 offset:35840
	ds_read_b128 v[218:221], v212 offset:36864
	ds_read_b128 v[222:225], v212 offset:37888
	ds_read_b128 v[226:229], v212 offset:38912
	ds_read_b128 v[230:233], v212 offset:39936
	global_load_lds_dwordx4 v2, s[18:19]
	s_mov_b32 m0, s50
	s_nop 0
	global_load_lds_dwordx4 v0, s[18:19]
	s_waitcnt vmcnt(8)
	s_waitcnt lgkmcnt(0)
	s_barrier
	s_setprio 1
	s_waitcnt lgkmcnt(0)
	v_mfma_f32_16x16x32_bf16 v[128:131], v[144:147], v[176:179], v[128:131]
	v_mfma_f32_16x16x32_bf16 v[124:127], v[152:155], v[176:179], v[124:127]
	v_mfma_f32_16x16x32_bf16 v[112:115], v[144:147], v[184:187], v[112:115]
	v_mfma_f32_16x16x32_bf16 v[108:111], v[152:155], v[184:187], v[108:111]
	v_mfma_f32_16x16x32_bf16 v[96:99], v[144:147], v[218:221], v[96:99]
	v_mfma_f32_16x16x32_bf16 v[92:95], v[152:155], v[218:221], v[92:95]
	v_mfma_f32_16x16x32_bf16 v[80:83], v[144:147], v[226:229], v[80:83]
	v_mfma_f32_16x16x32_bf16 v[76:79], v[152:155], v[226:229], v[76:79]
	v_mfma_f32_16x16x32_bf16 v[128:131], v[148:151], v[180:183], v[128:131]
	v_mfma_f32_16x16x32_bf16 v[124:127], v[156:159], v[180:183], v[124:127]
	v_mfma_f32_16x16x32_bf16 v[112:115], v[148:151], v[214:217], v[112:115]
	v_mfma_f32_16x16x32_bf16 v[108:111], v[156:159], v[214:217], v[108:111]
	v_mfma_f32_16x16x32_bf16 v[96:99], v[148:151], v[222:225], v[96:99]
	v_mfma_f32_16x16x32_bf16 v[92:95], v[156:159], v[222:225], v[92:95]
	v_mfma_f32_16x16x32_bf16 v[80:83], v[148:151], v[230:233], v[80:83]
	v_mfma_f32_16x16x32_bf16 v[76:79], v[156:159], v[230:233], v[76:79]
	s_setprio 0
	s_setprio 1
	v_mfma_f32_16x16x32_bf16 v[120:123], v[160:163], v[176:179], v[120:123]
	v_mfma_f32_16x16x32_bf16 v[116:119], v[168:171], v[176:179], v[116:119]
	v_mfma_f32_16x16x32_bf16 v[104:107], v[160:163], v[184:187], v[104:107]
	v_mfma_f32_16x16x32_bf16 v[100:103], v[168:171], v[184:187], v[100:103]
	v_mfma_f32_16x16x32_bf16 v[88:91], v[160:163], v[218:221], v[88:91]
	v_mfma_f32_16x16x32_bf16 v[84:87], v[168:171], v[218:221], v[84:87]
	v_mfma_f32_16x16x32_bf16 v[72:75], v[160:163], v[226:229], v[72:75]
	v_mfma_f32_16x16x32_bf16 v[68:71], v[168:171], v[226:229], v[68:71]
	v_mfma_f32_16x16x32_bf16 v[120:123], v[164:167], v[180:183], v[120:123]
	v_mfma_f32_16x16x32_bf16 v[116:119], v[172:175], v[180:183], v[116:119]
	v_mfma_f32_16x16x32_bf16 v[104:107], v[164:167], v[214:217], v[104:107]
	v_mfma_f32_16x16x32_bf16 v[100:103], v[172:175], v[214:217], v[100:103]
	v_mfma_f32_16x16x32_bf16 v[88:91], v[164:167], v[222:225], v[88:91]
	v_mfma_f32_16x16x32_bf16 v[84:87], v[172:175], v[222:225], v[84:87]
	v_mfma_f32_16x16x32_bf16 v[72:75], v[164:167], v[230:233], v[72:75]
	v_mfma_f32_16x16x32_bf16 v[68:71], v[172:175], v[230:233], v[68:71]
	s_setprio 0
	s_barrier
	s_add_i32 s18, s44, s46
	s_add_u32 s100, s22, 0x80
	s_addc_u32 s101, s23, 0
	s_mov_b32 m0, s18
	ds_read_b128 v[176:179], v212 offset:49152
	ds_read_b128 v[180:183], v212 offset:50176
	ds_read_b128 v[184:187], v212 offset:51200
	ds_read_b128 v[214:217], v212 offset:52224
	ds_read_b128 v[218:221], v212 offset:53248
	ds_read_b128 v[222:225], v212 offset:54272
	ds_read_b128 v[226:229], v212 offset:55296
	ds_read_b128 v[230:233], v212 offset:56320
	global_load_lds_dwordx4 v2, s[100:101]
	s_add_i32 m0, s18, 0x2000
	s_add_u32 s18, s22, 0xb0080
	s_addc_u32 s19, s23, 0
	s_add_i32 s22, s45, s46
	global_load_lds_dwordx4 v0, s[100:101]
	s_mov_b32 m0, s22
	s_nop 0
	global_load_lds_dwordx4 v2, s[18:19]
	s_add_i32 m0, s22, 0x2000
	s_nop 0
	global_load_lds_dwordx4 v0, s[18:19]
	s_add_u32 s100, s24, 0x80
	s_addc_u32 s101, s25, 0
	s_mov_b32 m0, s52
	s_nop 0
	global_load_lds_dwordx4 v2, s[100:101]
	s_mov_b32 m0, s53
	s_nop 0
	global_load_lds_dwordx4 v0, s[100:101]
	s_waitcnt vmcnt(8)
	s_waitcnt lgkmcnt(0)
	s_barrier
	s_setprio 1
	s_waitcnt lgkmcnt(0)
	v_mfma_f32_16x16x32_bf16 v[64:67], v[144:147], v[176:179], v[64:67]
	v_mfma_f32_16x16x32_bf16 v[60:63], v[152:155], v[176:179], v[60:63]
	v_mfma_f32_16x16x32_bf16 v[48:51], v[144:147], v[184:187], v[48:51]
	v_mfma_f32_16x16x32_bf16 v[44:47], v[152:155], v[184:187], v[44:47]
	v_mfma_f32_16x16x32_bf16 v[32:35], v[144:147], v[218:221], v[32:35]
	v_mfma_f32_16x16x32_bf16 v[28:31], v[152:155], v[218:221], v[28:31]
	v_mfma_f32_16x16x32_bf16 v[16:19], v[144:147], v[226:229], v[16:19]
	v_mfma_f32_16x16x32_bf16 v[12:15], v[152:155], v[226:229], v[12:15]
	v_mfma_f32_16x16x32_bf16 v[64:67], v[148:151], v[180:183], v[64:67]
	v_mfma_f32_16x16x32_bf16 v[60:63], v[156:159], v[180:183], v[60:63]
	v_mfma_f32_16x16x32_bf16 v[48:51], v[148:151], v[214:217], v[48:51]
	v_mfma_f32_16x16x32_bf16 v[44:47], v[156:159], v[214:217], v[44:47]
	v_mfma_f32_16x16x32_bf16 v[32:35], v[148:151], v[222:225], v[32:35]
	v_mfma_f32_16x16x32_bf16 v[28:31], v[156:159], v[222:225], v[28:31]
	v_mfma_f32_16x16x32_bf16 v[16:19], v[148:151], v[230:233], v[16:19]
	v_mfma_f32_16x16x32_bf16 v[12:15], v[156:159], v[230:233], v[12:15]
	s_setprio 0
	s_setprio 1
	v_mfma_f32_16x16x32_bf16 v[56:59], v[160:163], v[176:179], v[56:59]
	v_mfma_f32_16x16x32_bf16 v[52:55], v[168:171], v[176:179], v[52:55]
	v_mfma_f32_16x16x32_bf16 v[40:43], v[160:163], v[184:187], v[40:43]
	v_mfma_f32_16x16x32_bf16 v[36:39], v[168:171], v[184:187], v[36:39]
	v_mfma_f32_16x16x32_bf16 v[24:27], v[160:163], v[218:221], v[24:27]
	v_mfma_f32_16x16x32_bf16 v[20:23], v[168:171], v[218:221], v[20:23]
	v_mfma_f32_16x16x32_bf16 v[8:11], v[160:163], v[226:229], v[8:11]
	v_mfma_f32_16x16x32_bf16 v[4:7], v[168:171], v[226:229], v[4:7]
	v_mfma_f32_16x16x32_bf16 v[56:59], v[164:167], v[180:183], v[56:59]
	v_mfma_f32_16x16x32_bf16 v[52:55], v[172:175], v[180:183], v[52:55]
	v_mfma_f32_16x16x32_bf16 v[40:43], v[164:167], v[214:217], v[40:43]
	v_mfma_f32_16x16x32_bf16 v[36:39], v[172:175], v[214:217], v[36:39]
	v_mfma_f32_16x16x32_bf16 v[24:27], v[164:167], v[222:225], v[24:27]
	v_mfma_f32_16x16x32_bf16 v[20:23], v[172:175], v[222:225], v[20:23]
	v_mfma_f32_16x16x32_bf16 v[8:11], v[164:167], v[230:233], v[8:11]
	v_mfma_f32_16x16x32_bf16 v[4:7], v[172:175], v[230:233], v[4:7]
	s_setprio 0
	s_barrier
	s_add_i32 s15, s15, 2
	s_add_u32 s13, s13, 0x100
	s_addc_u32 s14, s14, 0
	s_cmp_gt_u32 s15, 41
	s_mov_b64 s[44:45], s[42:43]
	s_cbranch_scc0 .LBB0_811
	s_and_b64 vcc, exec, s[4:5]
	s_cbranch_vccz .LBB0_814
	s_barrier

.LBB0_927:
	s_ashr_i32 s7, s6, 31
	s_lshl_b64 s[10:11], s[6:7], 19
	s_add_u32 s10, s20, s10
	s_addc_u32 s11, s21, s11
	s_and_b64 s[14:15], s[38:39], exec
	s_cselect_b32 s7, s11, s23
	s_cselect_b32 s13, s10, s22
	s_ashr_i32 s5, s4, 31
	s_lshl_b64 s[14:15], s[4:5], 19
	s_add_u32 s14, s26, s14
	s_addc_u32 s15, s27, s15
	s_and_b64 s[18:19], s[38:39], exec
	s_cselect_b32 s5, s15, s43
	s_cselect_b32 s17, s14, s42
	s_add_u32 s40, s22, 0x40080
	s_addc_u32 s41, s23, 0
	s_add_u32 s42, s42, 0x100
	v_mov_b32_e32 v4, 0
	s_addc_u32 s43, s43, 0
	s_mov_b32 s51, -2
	v_mov_b32_e32 v5, v4
	v_mov_b32_e32 v6, v4
	v_mov_b32_e32 v7, v4
	v_mov_b32_e32 v8, v4
	v_mov_b32_e32 v9, v4
	v_mov_b32_e32 v10, v4
	v_mov_b32_e32 v11, v4
	v_mov_b32_e32 v16, v4
	v_mov_b32_e32 v17, v4
	v_mov_b32_e32 v18, v4
	v_mov_b32_e32 v19, v4
	v_mov_b32_e32 v24, v4
	v_mov_b32_e32 v25, v4
	v_mov_b32_e32 v26, v4
	v_mov_b32_e32 v27, v4
	v_mov_b32_e32 v32, v4
	v_mov_b32_e32 v33, v4
	v_mov_b32_e32 v34, v4
	v_mov_b32_e32 v35, v4
	v_mov_b32_e32 v40, v4
	v_mov_b32_e32 v41, v4
	v_mov_b32_e32 v42, v4
	v_mov_b32_e32 v43, v4
	v_mov_b32_e32 v48, v4
	v_mov_b32_e32 v49, v4
	v_mov_b32_e32 v50, v4
	v_mov_b32_e32 v51, v4
	v_mov_b32_e32 v56, v4
	v_mov_b32_e32 v57, v4
	v_mov_b32_e32 v58, v4
	v_mov_b32_e32 v59, v4
	v_mov_b32_e32 v12, v4
	v_mov_b32_e32 v13, v4
	v_mov_b32_e32 v14, v4
	v_mov_b32_e32 v15, v4
	v_mov_b32_e32 v20, v4
	v_mov_b32_e32 v21, v4
	v_mov_b32_e32 v22, v4
	v_mov_b32_e32 v23, v4
	v_mov_b32_e32 v28, v4
	v_mov_b32_e32 v29, v4
	v_mov_b32_e32 v30, v4
	v_mov_b32_e32 v31, v4
	v_mov_b32_e32 v36, v4
	v_mov_b32_e32 v37, v4
	v_mov_b32_e32 v38, v4
	v_mov_b32_e32 v39, v4
	v_mov_b32_e32 v44, v4
	v_mov_b32_e32 v45, v4
	v_mov_b32_e32 v46, v4
	v_mov_b32_e32 v47, v4
	v_mov_b32_e32 v52, v4
	v_mov_b32_e32 v53, v4
	v_mov_b32_e32 v54, v4
	v_mov_b32_e32 v55, v4
	v_mov_b32_e32 v60, v4
	v_mov_b32_e32 v61, v4
	v_mov_b32_e32 v62, v4
	v_mov_b32_e32 v63, v4
	v_mov_b32_e32 v64, v4
	v_mov_b32_e32 v65, v4
	v_mov_b32_e32 v66, v4
	v_mov_b32_e32 v67, v4
	v_mov_b32_e32 v68, v4
	v_mov_b32_e32 v69, v4
	v_mov_b32_e32 v70, v4
	v_mov_b32_e32 v71, v4
	v_mov_b32_e32 v72, v4
	v_mov_b32_e32 v73, v4
	v_mov_b32_e32 v74, v4
	v_mov_b32_e32 v75, v4
	v_mov_b32_e32 v80, v4
	v_mov_b32_e32 v81, v4
	v_mov_b32_e32 v82, v4
	v_mov_b32_e32 v83, v4
	v_mov_b32_e32 v88, v4
	v_mov_b32_e32 v89, v4
	v_mov_b32_e32 v90, v4
	v_mov_b32_e32 v91, v4
	v_mov_b32_e32 v96, v4
	v_mov_b32_e32 v97, v4
	v_mov_b32_e32 v98, v4
	v_mov_b32_e32 v99, v4
	v_mov_b32_e32 v104, v4
	v_mov_b32_e32 v105, v4
	v_mov_b32_e32 v106, v4
	v_mov_b32_e32 v107, v4
	v_mov_b32_e32 v112, v4
	v_mov_b32_e32 v113, v4
	v_mov_b32_e32 v114, v4
	v_mov_b32_e32 v115, v4
	v_mov_b32_e32 v120, v4
	v_mov_b32_e32 v121, v4
	v_mov_b32_e32 v122, v4
	v_mov_b32_e32 v123, v4
	v_mov_b32_e32 v76, v4
	v_mov_b32_e32 v77, v4
	v_mov_b32_e32 v78, v4
	v_mov_b32_e32 v79, v4
	v_mov_b32_e32 v84, v4
	v_mov_b32_e32 v85, v4
	v_mov_b32_e32 v86, v4
	v_mov_b32_e32 v87, v4
	v_mov_b32_e32 v92, v4
	v_mov_b32_e32 v93, v4
	v_mov_b32_e32 v94, v4
	v_mov_b32_e32 v95, v4
	v_mov_b32_e32 v100, v4
	v_mov_b32_e32 v101, v4
	v_mov_b32_e32 v102, v4
	v_mov_b32_e32 v103, v4
	v_mov_b32_e32 v108, v4
	v_mov_b32_e32 v109, v4
	v_mov_b32_e32 v110, v4
	v_mov_b32_e32 v111, v4
	v_mov_b32_e32 v116, v4
	v_mov_b32_e32 v117, v4
	v_mov_b32_e32 v118, v4
	v_mov_b32_e32 v119, v4
	v_mov_b32_e32 v124, v4
	v_mov_b32_e32 v125, v4
	v_mov_b32_e32 v126, v4
	v_mov_b32_e32 v127, v4
	v_mov_b32_e32 v128, v4
	v_mov_b32_e32 v129, v4
	v_mov_b32_e32 v130, v4
	v_mov_b32_e32 v131, v4
	v_add_u32_e32 v246, 0x10000, v152
.LBB0_928:
	s_add_u32 s18, s40, 0xfffc0080
	s_addc_u32 s19, s41, -1
	s_add_i32 s52, 0, 0x10000
	s_cmp_eq_u32 s51, 12
	s_cselect_b32 s25, s7, s19
	s_cselect_b32 s24, s13, s18
	s_cselect_b32 s23, s5, s43
	s_cselect_b32 s22, s17, s42
	s_add_i32 s53, 0, 0x14000
	ds_read_b128 v[148:151], v246
	ds_read_b128 v[158:161], v246 offset:1024
	ds_read_b128 v[162:165], v246 offset:2048
	ds_read_b128 v[166:169], v246 offset:3072
	ds_read_b128 v[170:173], v246 offset:16384
	ds_read_b128 v[174:177], v246 offset:17408
	ds_read_b128 v[178:181], v246 offset:18432
	ds_read_b128 v[182:185], v246 offset:19456
	s_add_i32 m0, s29, 0xc000
	ds_read_b128 v[186:189], v157
	ds_read_b128 v[208:211], v157 offset:1024
	ds_read_b128 v[212:215], v157 offset:2048
	ds_read_b128 v[216:219], v157 offset:3072
	ds_read_b128 v[220:223], v157 offset:4096
	ds_read_b128 v[224:227], v157 offset:5120
	ds_read_b128 v[228:231], v157 offset:6144
	ds_read_b128 v[232:235], v157 offset:7168
	global_load_lds_dwordx4 v144, s[40:41]
	s_add_i32 m0, s29, 0xe000
	s_nop 0
	global_load_lds_dwordx4 v146, s[40:41]
	s_waitcnt vmcnt(8)
	s_waitcnt lgkmcnt(0)
	s_barrier
	s_setprio 1
	s_waitcnt lgkmcnt(0)
	v_mfma_f32_16x16x32_bf16 v[128:131], v[148:151], v[186:189], v[128:131]
	v_mfma_f32_16x16x32_bf16 v[124:127], v[162:165], v[186:189], v[124:127]
	v_mfma_f32_16x16x32_bf16 v[116:119], v[148:151], v[212:215], v[116:119]
	v_mfma_f32_16x16x32_bf16 v[108:111], v[162:165], v[212:215], v[108:111]
	v_mfma_f32_16x16x32_bf16 v[100:103], v[148:151], v[220:223], v[100:103]
	v_mfma_f32_16x16x32_bf16 v[92:95], v[162:165], v[220:223], v[92:95]
	v_mfma_f32_16x16x32_bf16 v[84:87], v[148:151], v[228:231], v[84:87]
	v_mfma_f32_16x16x32_bf16 v[76:79], v[162:165], v[228:231], v[76:79]
	v_mfma_f32_16x16x32_bf16 v[128:131], v[158:161], v[208:211], v[128:131]
	v_mfma_f32_16x16x32_bf16 v[124:127], v[166:169], v[208:211], v[124:127]
	v_mfma_f32_16x16x32_bf16 v[116:119], v[158:161], v[216:219], v[116:119]
	v_mfma_f32_16x16x32_bf16 v[108:111], v[166:169], v[216:219], v[108:111]
	v_mfma_f32_16x16x32_bf16 v[100:103], v[158:161], v[224:227], v[100:103]
	v_mfma_f32_16x16x32_bf16 v[92:95], v[166:169], v[224:227], v[92:95]
	v_mfma_f32_16x16x32_bf16 v[84:87], v[158:161], v[232:235], v[84:87]
	v_mfma_f32_16x16x32_bf16 v[76:79], v[166:169], v[232:235], v[76:79]
	s_setprio 0
	s_setprio 1
	v_mfma_f32_16x16x32_bf16 v[120:123], v[170:173], v[186:189], v[120:123]
	v_mfma_f32_16x16x32_bf16 v[112:115], v[178:181], v[186:189], v[112:115]
	v_mfma_f32_16x16x32_bf16 v[104:107], v[170:173], v[212:215], v[104:107]
	v_mfma_f32_16x16x32_bf16 v[96:99], v[178:181], v[212:215], v[96:99]
	v_mfma_f32_16x16x32_bf16 v[88:91], v[170:173], v[220:223], v[88:91]
	v_mfma_f32_16x16x32_bf16 v[80:83], v[178:181], v[220:223], v[80:83]
	v_mfma_f32_16x16x32_bf16 v[72:75], v[170:173], v[228:231], v[72:75]
	v_mfma_f32_16x16x32_bf16 v[68:71], v[178:181], v[228:231], v[68:71]
	v_mfma_f32_16x16x32_bf16 v[120:123], v[174:177], v[208:211], v[120:123]
	v_mfma_f32_16x16x32_bf16 v[112:115], v[182:185], v[208:211], v[112:115]
	v_mfma_f32_16x16x32_bf16 v[104:107], v[174:177], v[216:219], v[104:107]
	v_mfma_f32_16x16x32_bf16 v[96:99], v[182:185], v[216:219], v[96:99]
	v_mfma_f32_16x16x32_bf16 v[88:91], v[174:177], v[224:227], v[88:91]
	v_mfma_f32_16x16x32_bf16 v[80:83], v[182:185], v[224:227], v[80:83]
	v_mfma_f32_16x16x32_bf16 v[72:75], v[174:177], v[232:235], v[72:75]
	v_mfma_f32_16x16x32_bf16 v[68:71], v[182:185], v[232:235], v[68:71]
	s_setprio 0
	s_barrier
	s_add_i32 s18, s52, s28
	s_mov_b32 m0, s18
	ds_read_b128 v[186:189], v157 offset:16384
	ds_read_b128 v[208:211], v157 offset:17408
	ds_read_b128 v[212:215], v157 offset:18432
	ds_read_b128 v[216:219], v157 offset:19456
	ds_read_b128 v[220:223], v157 offset:20480
	ds_read_b128 v[224:227], v157 offset:21504
	ds_read_b128 v[228:231], v157 offset:22528
	ds_read_b128 v[232:235], v157 offset:23552
	global_load_lds_dwordx4 v2, s[22:23]
	s_add_i32 m0, s18, 0x2000
	s_add_u32 s18, s22, 0x10000
	s_addc_u32 s19, s23, 0
	s_add_i32 s52, s53, s28
	global_load_lds_dwordx4 v142, s[22:23]
	s_mov_b32 m0, s52
	s_nop 0
	global_load_lds_dwordx4 v2, s[18:19]
	s_add_i32 m0, s52, 0x2000
	s_nop 0
	global_load_lds_dwordx4 v142, s[18:19]
	s_mov_b32 m0, s29
	s_nop 0
	global_load_lds_dwordx4 v0, s[24:25]
	s_mov_b32 m0, s44
	s_nop 0
	global_load_lds_dwordx4 v140, s[24:25]
	s_waitcnt vmcnt(8)
	s_waitcnt lgkmcnt(0)
	s_barrier
	s_setprio 1
	s_waitcnt lgkmcnt(0)
	v_mfma_f32_16x16x32_bf16 v[64:67], v[148:151], v[186:189], v[64:67]
	v_mfma_f32_16x16x32_bf16 v[60:63], v[162:165], v[186:189], v[60:63]
	v_mfma_f32_16x16x32_bf16 v[52:55], v[148:151], v[212:215], v[52:55]
	v_mfma_f32_16x16x32_bf16 v[44:47], v[162:165], v[212:215], v[44:47]
	v_mfma_f32_16x16x32_bf16 v[36:39], v[148:151], v[220:223], v[36:39]
	v_mfma_f32_16x16x32_bf16 v[28:31], v[162:165], v[220:223], v[28:31]
	v_mfma_f32_16x16x32_bf16 v[20:23], v[148:151], v[228:231], v[20:23]
	v_mfma_f32_16x16x32_bf16 v[12:15], v[162:165], v[228:231], v[12:15]
	v_mfma_f32_16x16x32_bf16 v[64:67], v[158:161], v[208:211], v[64:67]
	v_mfma_f32_16x16x32_bf16 v[60:63], v[166:169], v[208:211], v[60:63]
	v_mfma_f32_16x16x32_bf16 v[52:55], v[158:161], v[216:219], v[52:55]
	v_mfma_f32_16x16x32_bf16 v[44:47], v[166:169], v[216:219], v[44:47]
	v_mfma_f32_16x16x32_bf16 v[36:39], v[158:161], v[224:227], v[36:39]
	v_mfma_f32_16x16x32_bf16 v[28:31], v[166:169], v[224:227], v[28:31]
	v_mfma_f32_16x16x32_bf16 v[20:23], v[158:161], v[232:235], v[20:23]
	v_mfma_f32_16x16x32_bf16 v[12:15], v[166:169], v[232:235], v[12:15]
	s_setprio 0
	s_setprio 1
	v_mfma_f32_16x16x32_bf16 v[56:59], v[170:173], v[186:189], v[56:59]
	v_mfma_f32_16x16x32_bf16 v[48:51], v[178:181], v[186:189], v[48:51]
	v_mfma_f32_16x16x32_bf16 v[40:43], v[170:173], v[212:215], v[40:43]
	v_mfma_f32_16x16x32_bf16 v[32:35], v[178:181], v[212:215], v[32:35]
	v_mfma_f32_16x16x32_bf16 v[24:27], v[170:173], v[220:223], v[24:27]
	v_mfma_f32_16x16x32_bf16 v[16:19], v[178:181], v[220:223], v[16:19]
	v_mfma_f32_16x16x32_bf16 v[8:11], v[170:173], v[228:231], v[8:11]
	v_mfma_f32_16x16x32_bf16 v[4:7], v[178:181], v[228:231], v[4:7]
	v_mfma_f32_16x16x32_bf16 v[56:59], v[174:177], v[208:211], v[56:59]
	v_mfma_f32_16x16x32_bf16 v[48:51], v[182:185], v[208:211], v[48:51]
	v_mfma_f32_16x16x32_bf16 v[40:43], v[174:177], v[216:219], v[40:43]
	v_mfma_f32_16x16x32_bf16 v[32:35], v[182:185], v[216:219], v[32:35]
	v_mfma_f32_16x16x32_bf16 v[24:27], v[174:177], v[224:227], v[24:27]
	v_mfma_f32_16x16x32_bf16 v[16:19], v[182:185], v[224:227], v[16:19]
	v_mfma_f32_16x16x32_bf16 v[8:11], v[174:177], v[232:235], v[8:11]
	v_mfma_f32_16x16x32_bf16 v[4:7], v[182:185], v[232:235], v[4:7]
	s_setprio 0
	s_barrier
	s_add_i32 s52, 0, 0x18000
	s_add_i32 s53, 0, 0x1c000
	ds_read_b128 v[148:151], v246 offset:32768
	ds_read_b128 v[158:161], v246 offset:33792
	ds_read_b128 v[162:165], v246 offset:34816
	ds_read_b128 v[166:169], v246 offset:35840
	ds_read_b128 v[170:173], v246 offset:49152
	ds_read_b128 v[174:177], v246 offset:50176
	ds_read_b128 v[178:181], v246 offset:51200
	ds_read_b128 v[182:185], v246 offset:52224
	s_add_u32 s18, s24, 0x40000
	s_addc_u32 s19, s25, 0
	s_mov_b32 m0, s45
	ds_read_b128 v[186:189], v157 offset:32768
	ds_read_b128 v[208:211], v157 offset:33792
	ds_read_b128 v[212:215], v157 offset:34816
	ds_read_b128 v[216:219], v157 offset:35840
	ds_read_b128 v[220:223], v157 offset:36864
	ds_read_b128 v[224:227], v157 offset:37888
	ds_read_b128 v[228:231], v157 offset:38912
	ds_read_b128 v[232:235], v157 offset:39936
	global_load_lds_dwordx4 v0, s[18:19]
	s_mov_b32 m0, s46
	s_nop 0
	global_load_lds_dwordx4 v140, s[18:19]
	s_waitcnt vmcnt(8)
	s_waitcnt lgkmcnt(0)
	s_barrier
	s_setprio 1
	s_waitcnt lgkmcnt(0)
	v_mfma_f32_16x16x32_bf16 v[128:131], v[148:151], v[186:189], v[128:131]
	v_mfma_f32_16x16x32_bf16 v[124:127], v[162:165], v[186:189], v[124:127]
	v_mfma_f32_16x16x32_bf16 v[116:119], v[148:151], v[212:215], v[116:119]
	v_mfma_f32_16x16x32_bf16 v[108:111], v[162:165], v[212:215], v[108:111]
	v_mfma_f32_16x16x32_bf16 v[100:103], v[148:151], v[220:223], v[100:103]
	v_mfma_f32_16x16x32_bf16 v[92:95], v[162:165], v[220:223], v[92:95]
	v_mfma_f32_16x16x32_bf16 v[84:87], v[148:151], v[228:231], v[84:87]
	v_mfma_f32_16x16x32_bf16 v[76:79], v[162:165], v[228:231], v[76:79]
	v_mfma_f32_16x16x32_bf16 v[128:131], v[158:161], v[208:211], v[128:131]
	v_mfma_f32_16x16x32_bf16 v[124:127], v[166:169], v[208:211], v[124:127]
	v_mfma_f32_16x16x32_bf16 v[116:119], v[158:161], v[216:219], v[116:119]
	v_mfma_f32_16x16x32_bf16 v[108:111], v[166:169], v[216:219], v[108:111]
	v_mfma_f32_16x16x32_bf16 v[100:103], v[158:161], v[224:227], v[100:103]
	v_mfma_f32_16x16x32_bf16 v[92:95], v[166:169], v[224:227], v[92:95]
	v_mfma_f32_16x16x32_bf16 v[84:87], v[158:161], v[232:235], v[84:87]
	v_mfma_f32_16x16x32_bf16 v[76:79], v[166:169], v[232:235], v[76:79]
	s_setprio 0
	s_setprio 1
	v_mfma_f32_16x16x32_bf16 v[120:123], v[170:173], v[186:189], v[120:123]
	v_mfma_f32_16x16x32_bf16 v[112:115], v[178:181], v[186:189], v[112:115]
	v_mfma_f32_16x16x32_bf16 v[104:107], v[170:173], v[212:215], v[104:107]
	v_mfma_f32_16x16x32_bf16 v[96:99], v[178:181], v[212:215], v[96:99]
	v_mfma_f32_16x16x32_bf16 v[88:91], v[170:173], v[220:223], v[88:91]
	v_mfma_f32_16x16x32_bf16 v[80:83], v[178:181], v[220:223], v[80:83]
	v_mfma_f32_16x16x32_bf16 v[72:75], v[170:173], v[228:231], v[72:75]
	v_mfma_f32_16x16x32_bf16 v[68:71], v[178:181], v[228:231], v[68:71]
	v_mfma_f32_16x16x32_bf16 v[120:123], v[174:177], v[208:211], v[120:123]
	v_mfma_f32_16x16x32_bf16 v[112:115], v[182:185], v[208:211], v[112:115]
	v_mfma_f32_16x16x32_bf16 v[104:107], v[174:177], v[216:219], v[104:107]
	v_mfma_f32_16x16x32_bf16 v[96:99], v[182:185], v[216:219], v[96:99]
	v_mfma_f32_16x16x32_bf16 v[88:91], v[174:177], v[224:227], v[88:91]
	v_mfma_f32_16x16x32_bf16 v[80:83], v[182:185], v[224:227], v[80:83]
	v_mfma_f32_16x16x32_bf16 v[72:75], v[174:177], v[232:235], v[72:75]
	v_mfma_f32_16x16x32_bf16 v[68:71], v[182:185], v[232:235], v[68:71]
	s_setprio 0
	s_barrier
	s_add_i32 s18, s52, s28
	s_add_u32 s100, s22, 0x80
	s_addc_u32 s101, s23, 0
	s_mov_b32 m0, s18
	ds_read_b128 v[186:189], v157 offset:49152
	ds_read_b128 v[208:211], v157 offset:50176
	ds_read_b128 v[212:215], v157 offset:51200
	ds_read_b128 v[216:219], v157 offset:52224
	ds_read_b128 v[220:223], v157 offset:53248
	ds_read_b128 v[224:227], v157 offset:54272
	ds_read_b128 v[228:231], v157 offset:55296
	ds_read_b128 v[232:235], v157 offset:56320
	global_load_lds_dwordx4 v2, s[100:101]
	s_add_i32 m0, s18, 0x2000
	s_add_u32 s18, s22, 0x10080
	s_addc_u32 s19, s23, 0
	s_add_i32 s22, s53, s28
	global_load_lds_dwordx4 v142, s[100:101]
	s_mov_b32 m0, s22
	s_nop 0
	global_load_lds_dwordx4 v2, s[18:19]
	s_add_i32 m0, s22, 0x2000
	s_nop 0
	global_load_lds_dwordx4 v142, s[18:19]
	s_add_u32 s100, s24, 0x80
	s_addc_u32 s101, s25, 0
	s_mov_b32 m0, s47
	s_nop 0
	global_load_lds_dwordx4 v0, s[100:101]
	s_mov_b32 m0, s48
	s_nop 0
	global_load_lds_dwordx4 v140, s[100:101]
	s_waitcnt vmcnt(8)
	s_waitcnt lgkmcnt(0)
	s_barrier
	s_setprio 1
	s_waitcnt lgkmcnt(0)
	v_mfma_f32_16x16x32_bf16 v[64:67], v[148:151], v[186:189], v[64:67]
	v_mfma_f32_16x16x32_bf16 v[60:63], v[162:165], v[186:189], v[60:63]
	v_mfma_f32_16x16x32_bf16 v[52:55], v[148:151], v[212:215], v[52:55]
	v_mfma_f32_16x16x32_bf16 v[44:47], v[162:165], v[212:215], v[44:47]
	v_mfma_f32_16x16x32_bf16 v[36:39], v[148:151], v[220:223], v[36:39]
	v_mfma_f32_16x16x32_bf16 v[28:31], v[162:165], v[220:223], v[28:31]
	v_mfma_f32_16x16x32_bf16 v[20:23], v[148:151], v[228:231], v[20:23]
	v_mfma_f32_16x16x32_bf16 v[12:15], v[162:165], v[228:231], v[12:15]
	v_mfma_f32_16x16x32_bf16 v[64:67], v[158:161], v[208:211], v[64:67]
	v_mfma_f32_16x16x32_bf16 v[60:63], v[166:169], v[208:211], v[60:63]
	v_mfma_f32_16x16x32_bf16 v[52:55], v[158:161], v[216:219], v[52:55]
	v_mfma_f32_16x16x32_bf16 v[44:47], v[166:169], v[216:219], v[44:47]
	v_mfma_f32_16x16x32_bf16 v[36:39], v[158:161], v[224:227], v[36:39]
	v_mfma_f32_16x16x32_bf16 v[28:31], v[166:169], v[224:227], v[28:31]
	v_mfma_f32_16x16x32_bf16 v[20:23], v[158:161], v[232:235], v[20:23]
	v_mfma_f32_16x16x32_bf16 v[12:15], v[166:169], v[232:235], v[12:15]
	s_setprio 0
	s_setprio 1
	v_mfma_f32_16x16x32_bf16 v[56:59], v[170:173], v[186:189], v[56:59]
	v_mfma_f32_16x16x32_bf16 v[48:51], v[178:181], v[186:189], v[48:51]
	v_mfma_f32_16x16x32_bf16 v[40:43], v[170:173], v[212:215], v[40:43]
	v_mfma_f32_16x16x32_bf16 v[32:35], v[178:181], v[212:215], v[32:35]
	v_mfma_f32_16x16x32_bf16 v[24:27], v[170:173], v[220:223], v[24:27]
	v_mfma_f32_16x16x32_bf16 v[16:19], v[178:181], v[220:223], v[16:19]
	v_mfma_f32_16x16x32_bf16 v[8:11], v[170:173], v[228:231], v[8:11]
	v_mfma_f32_16x16x32_bf16 v[4:7], v[178:181], v[228:231], v[4:7]
	v_mfma_f32_16x16x32_bf16 v[56:59], v[174:177], v[208:211], v[56:59]
	v_mfma_f32_16x16x32_bf16 v[48:51], v[182:185], v[208:211], v[48:51]
	v_mfma_f32_16x16x32_bf16 v[40:43], v[174:177], v[216:219], v[40:43]
	v_mfma_f32_16x16x32_bf16 v[32:35], v[182:185], v[216:219], v[32:35]
	v_mfma_f32_16x16x32_bf16 v[24:27], v[174:177], v[224:227], v[24:27]
	v_mfma_f32_16x16x32_bf16 v[16:19], v[182:185], v[224:227], v[16:19]
	v_mfma_f32_16x16x32_bf16 v[8:11], v[174:177], v[232:235], v[8:11]
	v_mfma_f32_16x16x32_bf16 v[4:7], v[182:185], v[232:235], v[4:7]
	s_setprio 0
	s_barrier
	s_add_i32 s51, s51, 2
	s_add_u32 s40, s40, 0x100
	s_addc_u32 s41, s41, 0
	s_add_u32 s42, s42, 0x100
	s_addc_u32 s43, s43, 0
	s_cmp_gt_u32 s51, 13
	s_cbranch_scc0 .LBB0_928
	s_lshl_b32 s5, s16, 8
	s_and_b64 vcc, exec, s[2:3]
	s_cbranch_vccz .LBB0_931
	v_or_b32_e32 v148, s5, v154
	v_ashrrev_i32_e32 v149, 31, v148
	v_lshlrev_b64 v[148:149], 6, v[148:149]
	v_lshl_add_u64 v[166:167], s[74:75], 0, v[148:149]
	global_load_dwordx4 v[148:151], v[166:167], off
	global_load_dwordx4 v[158:161], v[166:167], off offset:32
	global_load_dwordx4 v[162:165], v[166:167], off offset:16
	s_nop 0
	global_load_dwordx4 v[166:169], v[166:167], off offset:48
	s_barrier
